# loop-edge edit: back edge of both attention loops rotated (loop-back barrier is the loop head; exit test, carried v_mov, counter and branch moved in front of it; exit path has its own barrier)
# speedup vs baseline: 1.0027x; 1.0027x over previous
; __device__ __forceinline__ int v_st(int k, int c) { const int kk = (k & ~0xC) | ((k & 4) << 1) | ((k & 8) >> 1); return ((kk >> 3) * 4 + (c >> 5)) * 512 + ((kk & 7) * 32 + (c & 31)) * 2; }
; __device__ __forceinline__ int v_rd_base(int lane) { return ((lane & 3) << 3) | (((lane >> 2) & 3) << 6) | (((lane >> 4) & 1) << 5) | (((lane >> 5) & 1) << 8); }
; template <int DQK, int DK1, int LDQ, int LDK, int LDKR, int LDV, int NQL, int SDEPTH>
; __device__ __forceinline__ void attn_core(const AttnArgs& a, char* lds, f32x16 (&o)[4]) {
;     ...
;     { const bf16_t* Qw = a.Q + (long)(wid * 32 + r32) * LDQ + hi * 8;
; #pragma unroll
;       for (int d0 = 0; d0 < NQR; ++d0) qr[d0] = *(const bf16x8*)(Qw + d0 * 16);
; #pragma unroll
;       for (int d0 = NQR; d0 < ND0; ++d0) *(bf16x8*)(QL + (d0 - NQR) * 8192) = *(const bf16x8*)(Qw + d0 * 16); }
;     const int sr = tid >> 4, sc = (tid & 15) * 8, vst0 = v_st(sr, sc), vst1 = v_st(32 + sr, sc);
;     const int vb0 = (int)(uintptr_t)V_lds + v_rd_base(lane);
;     const bf16_t* kptr[KCH]; int kld[KCH], kwo[KCH];
; #pragma unroll
;     for (int c = 0; c < KCH; ++c) { const int idx = tid + c * 512, kr_ = idx / CPR, kc = (idx % CPR) * 8;
;         if (kc < DK1) { kptr[c] = a.Kn + (long)kr_ * LDK + kc; kld[c] = LDK; } else { kptr[c] = a.Kr + (long)kr_ * LDKR + (kc - DK1); kld[c] = LDKR; }
;         kwo[c] = kr_ * KP + ((kc * 2) ^ ((kr_ & 7) << 4)); }
;     struct { bf16x8 vs0, vs1, ks[KCH]; } sr_[SDEPTH];
;     int kb[4];
; #pragma unroll
;     for (int m = 0; m < 4; ++m) kb[m] = r32 * KP + ((m * 32 + hi * 16) ^ ((r32 & 7) << 4));
.LBB0_170:
	v_mov_b32_e32 v14, v159
	s_xor_b64 s[94:95], s[14:15], -1
	s_lshl_b64 s[14:15], s[12:13], 1
	s_add_u32 s12, s87, s14
	v_ashrrev_i32_e32 v0, 31, v14
	v_lshrrev_b32_e32 v0, 29, v0
	s_addc_u32 s13, s68, s15
	v_add_u32_e32 v0, v14, v0
	s_add_u32 s14, s28, s14
	v_ashrrev_i32_e32 v16, 3, v0
	v_and_b32_e32 v0, -8, v0
	s_addc_u32 s15, s29, s15
	v_sub_u32_e32 v17, v14, v0
	v_ashrrev_i32_e32 v164, 4, v14
	v_lshlrev_b32_e32 v0, 3, v17
	v_mov_b64_e32 v[2:3], s[14:15]
	v_mad_i64_i32 v[2:3], s[14:15], v16, s9, v[2:3]
	v_ashrrev_i32_e32 v1, 31, v0
	v_ashrrev_i32_e32 v165, 31, v164
	v_lshlrev_b32_e32 v15, 3, v14
	v_lshl_add_u64 v[166:167], v[0:1], 1, v[2:3]
	v_lshl_add_u64 v[0:1], v[164:165], 0, s[18:19]
	v_mov_b64_e32 v[50:51], s[20:21]
	v_and_b32_e32 v4, 0x78, v15
	v_mad_u64_u32 v[2:3], s[14:15], v0, s9, v[50:51]
	v_mad_i32_i24 v3, v1, s9, v3
	v_lshlrev_b32_e32 v48, 1, v4
	v_mov_b32_e32 v49, v97
	v_lshl_add_u64 v[168:169], v[164:165], 0, 32
	v_lshl_add_u64 v[0:1], v[2:3], 0, v[48:49]
	v_lshl_add_u64 v[2:3], v[168:169], 0, s[18:19]
	v_mad_u64_u32 v[4:5], s[14:15], v2, s9, v[50:51]
	v_mad_i32_i24 v5, v3, s9, v5
	v_lshl_add_u64 v[4:5], v[4:5], 0, v[48:49]
	global_load_dwordx4 v[0:3], v[0:1], off
	s_nop 0
	global_load_dwordx4 v[4:7], v[4:5], off
	v_ashrrev_i32_e32 v12, 1, v14
	v_lshl_add_u64 v[8:9], v[166:167], 0, s[22:23]
	v_bfi_b32 v18, s33, v12, v14
	v_mov_b64_e32 v[12:13], s[12:13]
	global_load_dwordx4 v[8:11], v[8:9], off
	v_mad_i64_i32 v[12:13], s[12:13], v18, s9, v[12:13]
	v_lshrrev_b32_e32 v18, 1, v14
	v_and_b32_e32 v96, 16, v18
	v_lshl_add_u64 v[12:13], v[12:13], 0, v[96:97]
	global_load_dwordx4 v[110:113], v[12:13], off
	global_load_dwordx4 v[106:109], v[12:13], off offset:32
	global_load_dwordx4 v[102:105], v[12:13], off offset:64
	global_load_dwordx4 v[98:101], v[12:13], off offset:96
	v_and_b32_e32 v18, 0xfffff0, v164
	v_lshlrev_b32_e32 v19, 1, v164
	v_lshrrev_b32_e32 v20, 1, v164
	v_and_b32_e32 v21, 3, v164
	v_add_u32_e32 v22, 32, v164
	v_and_or_b32 v18, v19, 8, v18
	v_and_or_b32 v19, v20, 4, v21
	v_and_b32_e32 v20, 0xfffff0, v22
	v_lshlrev_b32_e32 v21, 1, v22
	v_bfe_u32 v15, v15, 5, 2
	v_lshrrev_b32_e32 v18, 1, v18
	v_and_or_b32 v20, v21, 8, v20
	v_and_b32_e32 v68, 31, v14
	v_lshlrev_b32_e32 v52, 4, v14
	v_or_b32_e32 v12, v18, v15
	v_lshrrev_b32_e32 v13, 1, v20
	v_lshlrev_b32_e32 v53, 7, v68
	v_and_b32_e32 v54, 0x70, v52
	v_and_b32_e32 v23, 48, v52
	v_lshlrev_b32_e32 v19, 6, v19
	v_lshlrev_b32_e32 v12, 9, v12
	v_or_b32_e32 v13, v13, v15
	v_bitop3_b32 v22, v96, v53, v54 bitop3:0xde
	v_lshlrev_b32_e32 v18, 7, v16
	v_bitop3_b32 v15, v16, v17, 7 bitop3:0x6c
	v_lshlrev_b32_e32 v13, 9, v13
	v_or3_b32 v12, v12, v19, v23
	v_lshl_add_u32 v15, v15, 4, v18
	v_or3_b32 v13, v13, v19, v23
	v_add_u32_e32 v181, 0, v12
	v_add_u32_e32 v186, 0, v22
	v_add_u32_e32 v182, 0, v15
	v_add_u32_e32 v184, 0, v13
	s_waitcnt vmcnt(0)
	v_and_b32_e32 v69, 63, v14
	v_lshl_add_u64 v[64:65], v[164:165], 0, s[88:89]
	v_mad_u64_u32 v[66:67], s[12:13], v64, s9, v[50:51]
	v_mad_i32_i24 v67, v65, s9, v67
	v_lshl_add_u64 v[60:61], v[166:167], 0, s[78:79]
	v_lshl_add_u64 v[64:65], v[66:67], 0, v[48:49]
	s_cmp_lg_u32 0, -1
	s_cselect_b32 s14, 0, 0
	s_waitcnt vmcnt(0)
	ds_write_b128 v181, v[0:3]
	s_waitcnt vmcnt(5)
	ds_write_b128 v184, v[4:7]
	s_waitcnt vmcnt(4)
	ds_write_b128 v182, v[8:11] offset:32768
	s_waitcnt lgkmcnt(0)
	s_barrier
	ds_read_b128 v[0:3], v186 offset:32768
	ds_read_b128 v[4:7], v186 offset:36864
	s_waitcnt vmcnt(3) lgkmcnt(1)
	v_mfma_f32_32x32x16_bf16 v[32:47], v[0:3], v[110:113], 0
	v_or_b32_e32 v0, 32, v96
	v_bitop3_b32 v0, v0, v53, v54 bitop3:0xde
	v_add_u32_e32 v188, 0, v0
	ds_read_b128 v[0:3], v188 offset:32768
	v_and_b32_e32 v8, 0x3fffffc0, v14
	v_lshl_add_u32 v161, v8, 2, 0
	v_lshlrev_b32_e32 v8, 3, v69
	s_waitcnt lgkmcnt(1)
	v_mfma_f32_32x32x16_bf16 v[16:31], v[4:7], v[110:113], 0
	ds_read_b128 v[4:7], v188 offset:36864
	s_mov_b32 s37, s36
	s_mov_b32 s38, s36
	s_mov_b32 s39, s36
	s_mov_b32 s40, s36
	s_mov_b32 s41, s36
	s_mov_b32 s42, s36
	s_waitcnt vmcnt(2) lgkmcnt(1)
	v_mfma_f32_32x32x16_bf16 v[32:47], v[0:3], v[106:109], v[32:47]
	v_or_b32_e32 v0, 64, v96
	v_bitop3_b32 v0, v0, v53, v54 bitop3:0xde
	v_add_u32_e32 v190, 0, v0
	ds_read_b128 v[0:3], v190 offset:32768
	s_mov_b32 s43, s36
	s_mov_b32 s44, s36
	s_mov_b32 s45, s36
	s_waitcnt lgkmcnt(1)
	v_mfma_f32_32x32x16_bf16 v[16:31], v[4:7], v[106:109], v[16:31]
	v_and_b32_e32 v4, 0xc0, v52
	v_lshlrev_b32_e32 v5, 1, v14
	v_and_or_b32 v4, v8, 24, v4
	v_and_b32_e32 v5, 32, v5
	v_and_b32_e32 v6, 0x100, v8
	v_or3_b32 v70, v4, v5, v6
	ds_read_b128 v[4:7], v190 offset:36864
	s_waitcnt vmcnt(1) lgkmcnt(1)
	v_mfma_f32_32x32x16_bf16 v[32:47], v[0:3], v[102:105], v[32:47]
	v_or_b32_e32 v0, 0x60, v96
	v_bitop3_b32 v0, v0, v53, v54 bitop3:0xde
	v_add_u32_e32 v192, 0, v0
	ds_read_b128 v[0:3], v192 offset:32768
	ds_read_b128 v[52:55], v192 offset:36864
	s_mov_b32 s46, s36
	s_mov_b32 s47, s36
	s_waitcnt lgkmcnt(2)
	v_mfma_f32_32x32x16_bf16 v[16:31], v[4:7], v[102:105], v[16:31]
	s_mov_b32 s48, s36
	s_mov_b32 s49, s36
	s_mov_b32 s50, s36
	s_mov_b32 s51, s36
	v_add_u32_e32 v180, s14, v70
	v_lshl_add_u64 v[170:171], s[20:21], 0, v[48:49]
	s_mov_b32 s52, 4
	s_waitcnt vmcnt(0) lgkmcnt(1)
	v_mfma_f32_32x32x16_bf16 v[32:47], v[0:3], v[98:101], v[32:47]
	v_mov_b64_e32 v[0:1], s[36:37]
	v_mov_b64_e32 v[14:15], s[50:51]
	v_mov_b64_e32 v[2:3], s[38:39]
	v_mov_b64_e32 v[4:5], s[40:41]
	v_mov_b64_e32 v[6:7], s[42:43]
	v_mov_b64_e32 v[8:9], s[44:45]
	v_mov_b64_e32 v[10:11], s[46:47]
	s_waitcnt lgkmcnt(0)
; #define SLOAD(i, j) do { const long rb_ = KROW(j); sr_[i].vs0 = *(const bf16x8*)(a.V + (rb_ + sr) * LDV + sc); sr_[i].vs1 = *(const bf16x8*)(a.V + (rb_ + 32 + sr) * LDV + sc); \
;     _Pragma("unroll") for (int c_ = 0; c_ < KCH; ++c_) sr_[i].ks[c_] = *(const bf16x8*)(kptr[c_] + rb_ * kld[c_]); } while (0)
; #define SWRITE(b, i) do { *(bf16x8*)(V_lds + (b) * SHM_V + vst0) = sr_[i].vs0; *(bf16x8*)(V_lds + (b) * SHM_V + vst1) = sr_[i].vs1; \
;     _Pragma("unroll") for (int c_ = 0; c_ < KCH; ++c_) *(bf16x8*)(K_lds + (b) * SHM_K + kwo[c_]) = sr_[i].ks[c_]; } while (0)
; __device__ __forceinline__ void partialSM(f32x16& p0, f32x16& p1, float& m_reg, float& mn, float& alpha, const float C, const float thr) {
;     float pmax = p0[0];
; #pragma unroll
;     for (int r = 1; r < 16; ++r) pmax = fmaxf(pmax, p0[r]);
; #pragma unroll
;     for (int r = 0; r < 16; ++r) pmax = fmaxf(pmax, p1[r]);
;     { auto rr = __builtin_amdgcn_permlane32_swap(__float_as_uint(pmax), __float_as_uint(pmax), false, false);
;       pmax = fmaxf(__uint_as_float(rr[0]), __uint_as_float(rr[1])); }
;     if (__builtin_expect(__all(pmax - m_reg <= thr), 1)) { mn = m_reg; alpha = 1.f; }
;     else { mn = fmaxf(m_reg, pmax); alpha = __builtin_amdgcn_exp2f((m_reg - mn) * C); m_reg = mn; }
;     const float mnC = -mn * C;
; #pragma unroll
;     for (int r = 0; r < 16; ++r) p0[r] = fmaf(p0[r], C, mnC);
; #pragma unroll
;     for (int r = 0; r < 16; ++r) p1[r] = fmaf(p1[r], C, mnC);
; #pragma unroll
;     for (int r = 0; r < 16; ++r) p0[r] = __builtin_amdgcn_exp2f(p0[r]);
; }
; template <int DQK, int DK1, int LDQ, int LDK, int LDKR, int LDV, int NQL, int SDEPTH>
; __device__ __forceinline__ void attn_core(const AttnArgs& a, char* lds, f32x16 (&o)[4]) {
;     ...
;     SLOAD(SO, 1); if (SDEPTH == 2 && 2 < NT) SLOAD(SE, 2);
;     SWRITE(1, SO); __syncthreads();
	v_mfma_f32_32x32x16_bf16 v[16:31], v[52:55], v[98:101], v[16:31]
	s_nop 2
	v_max_f32_e32 v52, v33, v33
	v_max_f32_e32 v53, v32, v32
	v_max_f32_e32 v52, v53, v52
	v_max3_f32 v52, v52, v34, v35
	v_max3_f32 v52, v52, v36, v37
	v_max3_f32 v52, v52, v38, v39
	v_max3_f32 v52, v52, v40, v41
	v_max3_f32 v52, v52, v42, v43
	v_max3_f32 v52, v52, v44, v45
	v_max3_f32 v52, v52, v46, v47
	v_max3_f32 v52, v52, v16, v17
	v_max3_f32 v71, v52, v18, v19
	v_lshl_add_u64 v[52:53], v[164:165], 0, s[24:25]
	v_mad_u64_u32 v[54:55], s[12:13], v52, s9, v[50:51]
	v_mad_i32_i24 v55, v53, s9, v55
	v_lshl_add_u64 v[52:53], v[54:55], 0, v[48:49]
	v_lshl_add_u64 v[54:55], v[168:169], 0, s[24:25]
	v_mad_u64_u32 v[56:57], s[12:13], v54, s9, v[50:51]
	v_mad_i32_i24 v57, v55, s9, v57
	v_lshl_add_u64 v[56:57], v[56:57], 0, v[48:49]
	global_load_dwordx4 v[52:55], v[52:53], off
	s_nop 0
	global_load_dwordx4 v[56:59], v[56:57], off
	v_mov_b64_e32 v[12:13], s[48:49]
	global_load_dwordx4 v[60:63], v[60:61], off
	v_lshl_add_u32 v177, v68, 2, v161
	global_load_dwordx4 v[114:117], v[64:65], off
	v_lshl_add_u64 v[64:65], v[168:169], 0, s[88:89]
	v_mad_u64_u32 v[50:51], s[12:13], v64, s9, v[50:51]
	v_mad_i32_i24 v51, v65, s9, v51
	v_lshl_add_u64 v[50:51], v[50:51], 0, v[48:49]
	v_lshl_add_u64 v[64:65], v[166:167], 0, s[90:91]
	global_load_dwordx4 v[118:121], v[50:51], off
	global_load_dwordx4 v[122:125], v[64:65], off
	v_max3_f32 v50, v71, v20, v21
	v_max3_f32 v50, v50, v22, v23
	v_max3_f32 v50, v50, v24, v25
	v_max3_f32 v50, v50, v26, v27
	v_max3_f32 v50, v50, v28, v29
	v_max3_f32 v50, v50, v30, v31
	v_mov_b32_e32 v51, v50
	s_nop 1
	v_permlane32_swap_b32_e32 v50, v51
	v_max_f32_e32 v51, v51, v51
	v_max_f32_e32 v50, v50, v50
	v_max_f32_e32 v50, v50, v51
	v_add_f32_e32 v51, 0x7149f2ca, v50
	v_max_f32_e32 v50, 0xf149f2ca, v50
	v_cmp_ge_f32_e32 vcc, s76, v51
	v_sub_f32_e32 v51, 0xf149f2ca, v50
	v_mul_f32_e32 v51, 0x3e38aa3b, v51
	v_exp_f32_e32 v51, v51
	s_cmp_eq_u64 vcc, exec
	s_cselect_b64 vcc, -1, 0
	v_cndmask_b32_e32 v142, v50, v193, vcc
	v_mul_f32_e32 v50, 0xbe38aa3b, v142
	v_cndmask_b32_e64 v194, v51, 1.0, vcc
	v_mov_b32_e32 v51, v50
	v_fmamk_f32 v32, v32, 0x3e38aa3b, v50
	v_fmamk_f32 v33, v33, 0x3e38aa3b, v50
	v_fmamk_f32 v34, v34, 0x3e38aa3b, v50
	v_fmamk_f32 v35, v35, 0x3e38aa3b, v50
	v_fmamk_f32 v36, v36, 0x3e38aa3b, v50
	v_fmamk_f32 v37, v37, 0x3e38aa3b, v50
	v_fmamk_f32 v38, v38, 0x3e38aa3b, v50
	v_fmamk_f32 v39, v39, 0x3e38aa3b, v50
	v_fmamk_f32 v40, v40, 0x3e38aa3b, v50
	v_fmamk_f32 v41, v41, 0x3e38aa3b, v50
	v_fmamk_f32 v42, v42, 0x3e38aa3b, v50
	v_fmamk_f32 v43, v43, 0x3e38aa3b, v50
	v_fmamk_f32 v44, v44, 0x3e38aa3b, v50
	v_fmamk_f32 v45, v45, 0x3e38aa3b, v50
	v_fmamk_f32 v46, v46, 0x3e38aa3b, v50
	v_fmac_f32_e32 v51, 0x3e38aa3b, v47
	v_exp_f32_e32 v217, v32
	v_exp_f32_e32 v219, v33
	v_exp_f32_e32 v208, v34
	v_exp_f32_e32 v218, v35
	v_exp_f32_e32 v153, v36
	v_exp_f32_e32 v216, v37
	v_exp_f32_e32 v152, v38
	v_exp_f32_e32 v202, v39
	v_exp_f32_e32 v149, v40
	v_exp_f32_e32 v151, v41
	v_exp_f32_e32 v147, v42
	v_exp_f32_e32 v150, v43
	v_exp_f32_e32 v145, v44
	v_exp_f32_e32 v148, v45
	v_exp_f32_e32 v144, v46
	v_exp_f32_e32 v146, v51
	v_pk_fma_f32 v[132:133], v[30:31], s[8:9], v[50:51] op_sel_hi:[1,0,0]
	v_pk_fma_f32 v[134:135], v[28:29], s[8:9], v[50:51] op_sel_hi:[1,0,0]
	v_pk_fma_f32 v[140:141], v[26:27], s[8:9], v[50:51] op_sel_hi:[1,0,0]
	v_pk_fma_f32 v[126:127], v[24:25], s[8:9], v[50:51] op_sel_hi:[1,0,0]
	v_pk_fma_f32 v[128:129], v[22:23], s[8:9], v[50:51] op_sel_hi:[1,0,0]
	v_pk_fma_f32 v[130:131], v[20:21], s[8:9], v[50:51] op_sel_hi:[1,0,0]
	v_pk_fma_f32 v[136:137], v[18:19], s[8:9], v[50:51] op_sel_hi:[1,0,0]
	v_pk_fma_f32 v[138:139], v[16:17], s[8:9], v[50:51] op_sel_hi:[1,0,0]
	s_waitcnt vmcnt(5)
	ds_write_b128 v181, v[52:55] offset:16384
	s_waitcnt vmcnt(4)
	ds_write_b128 v184, v[56:59] offset:16384
	s_waitcnt vmcnt(3)
	ds_write_b128 v182, v[60:63] offset:40960
	s_addk_i32 s14, 0x4000
	v_mov_b64_e32 v[30:31], v[14:15]
	v_mov_b64_e32 v[46:47], v[14:15]
	v_mov_b64_e32 v[62:63], v[14:15]
	v_cmp_gt_u32_e64 s[12:13], 32, v69
	v_add_u32_e32 v179, s14, v70
	v_mov_b32_e32 v178, 0
	v_mov_b64_e32 v[28:29], v[12:13]
	v_mov_b64_e32 v[26:27], v[10:11]
	v_mov_b64_e32 v[24:25], v[8:9]
	v_mov_b64_e32 v[22:23], v[6:7]
	v_mov_b64_e32 v[20:21], v[4:5]
	v_mov_b64_e32 v[18:19], v[2:3]
	v_mov_b64_e32 v[16:17], v[0:1]
	v_mov_b64_e32 v[44:45], v[12:13]
	v_mov_b64_e32 v[42:43], v[10:11]
	v_mov_b64_e32 v[40:41], v[8:9]
	v_mov_b64_e32 v[38:39], v[6:7]
	v_mov_b64_e32 v[36:37], v[4:5]
	v_mov_b64_e32 v[34:35], v[2:3]
	v_mov_b64_e32 v[32:33], v[0:1]
	v_mov_b64_e32 v[60:61], v[12:13]
	v_mov_b64_e32 v[58:59], v[10:11]
	v_mov_b64_e32 v[56:57], v[8:9]
	v_mov_b64_e32 v[54:55], v[6:7]
	v_mov_b64_e32 v[52:53], v[4:5]
	v_mov_b64_e32 v[50:51], v[2:3]
	v_mov_b64_e32 v[48:49], v[0:1]
	s_waitcnt lgkmcnt(0)
	s_add_i32 s37, s52, -3
; #define SBAR() __builtin_amdgcn_sched_barrier(0)
; #define SLOAD(i, j) do { const long rb_ = KROW(j); sr_[i].vs0 = *(const bf16x8*)(a.V + (rb_ + sr) * LDV + sc); sr_[i].vs1 = *(const bf16x8*)(a.V + (rb_ + 32 + sr) * LDV + sc); \
;     _Pragma("unroll") for (int c_ = 0; c_ < KCH; ++c_) sr_[i].ks[c_] = *(const bf16x8*)(kptr[c_] + rb_ * kld[c_]); } while (0)
; __device__ __forceinline__ void finishSM(f32x16& p0, f32x16& p1, float alpha, float& l_reg, bf16x8& pa0, bf16x8& pa1, bf16x8& pa2, bf16x8& pa3) {
; #pragma unroll
;     for (int r = 0; r < 16; ++r) p1[r] = __builtin_amdgcn_exp2f(p1[r]);
;     float ps = 0;
; #pragma unroll
;     for (int r = 0; r < 16; ++r) ps += p0[r];
; #pragma unroll
;     for (int r = 0; r < 16; ++r) ps += p1[r];
;     { auto rr = __builtin_amdgcn_permlane32_swap(__float_as_uint(ps), __float_as_uint(ps), false, false);
;       ps = __uint_as_float(rr[0]) + __uint_as_float(rr[1]); }
;     l_reg = l_reg * alpha + ps;
;     ...
;     PK4(p0, 0, pa0); PK4(p0, 8, pa1); PK4(p1, 0, pa2); PK4(p1, 8, pa3);
;     ...
; }
; template <int DQK, int DK1, int LDQ, int LDK, int LDKR, int LDV, int NQL, int SDEPTH>
; __device__ __forceinline__ void attn_core(const AttnArgs& a, char* lds, f32x16 (&o)[4]) {
;     ...
;     for (int j = 1; j + 1 < NT; j += 2) {
;         SBAR(); QKT(pB0, pB1, K_lds + SHM_K);
;         finishSM(pA0, pA1, alA, l_reg, pa0, pa1, pa2, pa3); SBAR();
;         SLOAD(SO, j + SDEPTH); SBAR();
;         pv_d0(o, vb0, pa0, pa1, pa2, pa3); partialSM(pB0, pB1, m_reg, mnB, alB, a.C, a.thr);
.LBB0_171:
	s_barrier
	ds_read_b128 v[64:67], v186 offset:40960
	ds_read_b128 v[68:71], v186 offset:45056
	v_exp_f32_e32 v143, v138
	v_add_f32_e32 v138, 0, v217
	v_add_f32_e32 v138, v219, v138
	s_waitcnt lgkmcnt(1)
	v_mfma_f32_32x32x16_bf16 v[80:95], v[64:67], v[110:113], 0
	v_add_f32_e32 v138, v208, v138
	v_add_f32_e32 v138, v218, v138
	v_add_f32_e32 v138, v153, v138
	ds_read_b128 v[204:207], v188 offset:40960
	ds_read_b128 v[220:223], v188 offset:45056
	v_add_f32_e32 v138, v216, v138
	v_add_f32_e32 v138, v152, v138
	v_add_f32_e32 v138, v202, v138
	s_waitcnt lgkmcnt(2)
	v_mfma_f32_32x32x16_bf16 v[64:79], v[68:71], v[110:113], 0
	v_add_f32_e32 v138, v149, v138
	v_add_f32_e32 v138, v151, v138
	v_add_f32_e32 v138, v147, v138
	v_add_f32_e32 v138, v150, v138
	v_add_f32_e32 v138, v145, v138
	v_exp_f32_e32 v191, v139
	v_add_f32_e32 v138, v148, v138
	s_waitcnt lgkmcnt(1)
	v_mfma_f32_32x32x16_bf16 v[80:95], v[204:207], v[106:109], v[80:95]
	v_exp_f32_e32 v136, v136
	v_add_f32_e32 v138, v144, v138
	v_exp_f32_e32 v137, v137
	v_add_f32_e32 v138, v146, v138
	v_exp_f32_e32 v130, v130
	v_add_f32_e32 v138, v143, v138
	v_exp_f32_e32 v131, v131
	s_waitcnt lgkmcnt(0)
	v_mfma_f32_32x32x16_bf16 v[64:79], v[220:223], v[106:109], v[64:79]
	ds_read_b128 v[204:207], v190 offset:40960
	ds_read_b128 v[220:223], v190 offset:45056
	v_add_f32_e32 v138, v191, v138
	v_exp_f32_e32 v128, v128
	v_add_f32_e32 v138, v136, v138
	v_exp_f32_e32 v129, v129
	v_add_f32_e32 v138, v137, v138
	v_exp_f32_e32 v126, v126
	s_waitcnt lgkmcnt(1)
	v_mfma_f32_32x32x16_bf16 v[80:95], v[204:207], v[102:105], v[80:95]
	v_add_f32_e32 v138, v130, v138
	v_exp_f32_e32 v127, v127
	v_add_f32_e32 v138, v131, v138
	v_exp_f32_e32 v200, v140
	v_add_f32_e32 v138, v128, v138
	v_exp_f32_e32 v210, v141
	v_add_f32_e32 v138, v129, v138
	s_waitcnt lgkmcnt(0)
	v_mfma_f32_32x32x16_bf16 v[64:79], v[220:223], v[102:105], v[64:79]
	ds_read_b128 v[204:207], v192 offset:40960
	ds_read_b128 v[220:223], v192 offset:45056
	v_exp_f32_e32 v134, v134
	v_add_f32_e32 v138, v126, v138
	v_exp_f32_e32 v135, v135
	v_add_f32_e32 v138, v127, v138
	v_exp_f32_e32 v132, v132
	v_add_f32_e32 v138, v200, v138
	s_waitcnt lgkmcnt(1)
	v_mfma_f32_32x32x16_bf16 v[80:95], v[204:207], v[98:101], v[80:95]
	v_exp_f32_e32 v133, v133
	v_add_f32_e32 v138, v210, v138
	v_add_f32_e32 v138, v134, v138
	v_add_f32_e32 v138, v135, v138
	v_add_f32_e32 v138, v132, v138
	v_add_f32_e32 v196, v133, v138
	v_mov_b32_e32 v198, v196
	s_waitcnt lgkmcnt(0)
	v_mfma_f32_32x32x16_bf16 v[64:79], v[220:223], v[98:101], v[64:79]
	ds_read_b64_tr_b16 v[220:221], v180 offset:0x1000
	ds_read_b64_tr_b16 v[222:223], v180 offset:0x1800
	ds_read_b64_tr_b16 v[224:225], v180 offset:0x2000
	ds_read_b64_tr_b16 v[226:227], v180 offset:0x2800
	ds_read_b64_tr_b16 v[228:229], v180 offset:0x3000
	ds_read_b64_tr_b16 v[230:231], v180 offset:0x3800
	v_cvt_pk_bf16_f32 v138, v217, v219
	v_cvt_pk_bf16_f32 v139, v208, v218
	v_cvt_pk_bf16_f32 v140, v153, v216
	ds_read_b64_tr_b16 v[216:217], v180 offset:0
	ds_read_b64_tr_b16 v[218:219], v180 offset:0x800
	v_permlane32_swap_b32_e32 v196, v198
	v_cvt_pk_bf16_f32 v141, v152, v202
	v_permlane32_swap_b32_e32 v138, v140
	v_cvt_pk_bf16_f32 v204, v149, v151
	v_cvt_pk_bf16_f32 v205, v147, v150
	v_cvt_pk_bf16_f32 v206, v145, v148
	v_cvt_pk_bf16_f32 v207, v144, v146
	v_cvt_pk_bf16_f32 v144, v143, v191
	v_cvt_pk_bf16_f32 v145, v136, v137
	v_cvt_pk_bf16_f32 v146, v130, v131
	v_cvt_pk_bf16_f32 v147, v128, v129
	v_cvt_pk_bf16_f32 v148, v126, v127
	v_cvt_pk_bf16_f32 v149, v200, v210
	v_cvt_pk_bf16_f32 v150, v134, v135
	v_cvt_pk_bf16_f32 v151, v132, v133
	v_permlane32_swap_b32_e32 v139, v141
	v_permlane32_swap_b32_e32 v204, v206
	v_permlane32_swap_b32_e32 v205, v207
	v_permlane32_swap_b32_e32 v144, v146
	v_permlane32_swap_b32_e32 v145, v147
	v_permlane32_swap_b32_e32 v148, v150
	v_permlane32_swap_b32_e32 v149, v151
	s_cmp_lt_u32 s37, 30
	s_cselect_b32 s14, 0, 0xffffffe0
	s_cselect_b32 s15, s18, s86
	s_add_i32 s14, s14, s52
	s_lshl_b32 s14, s14, 6
	s_add_i32 s14, s14, s15
	s_sub_i32 s14, s14, 64
	s_ashr_i32 s15, s14, 31
	v_lshl_add_u64 v[126:127], s[14:15], 0, v[164:165]
	v_lshl_add_u64 v[130:131], v[168:169], 0, s[14:15]
	v_mad_u64_u32 v[128:129], s[38:39], v126, s9, v[170:171]
	v_mad_u64_u32 v[132:133], s[38:39], v130, s9, v[170:171]
	v_mad_i32_i24 v129, v127, s9, v129
	v_mad_i32_i24 v133, v131, s9, v133
	v_mad_i64_i32 v[134:135], s[14:15], s14, v195, v[166:167]
	global_load_dwordx4 v[126:129], v[128:129], off
	s_nop 0
	global_load_dwordx4 v[130:133], v[132:133], off
	s_nop 0
	global_load_dwordx4 v[134:137], v[134:135], off
	s_waitcnt lgkmcnt(0)
	s_nop 0
	v_mfma_f32_32x32x16_bf16 v[48:63], v[138:141], v[216:219], v[48:63]
	ds_read_b64_tr_b16 v[216:217], v180 offset:0x200
	ds_read_b64_tr_b16 v[218:219], v180 offset:0xa00
	v_max_f32_e32 v238, v81, v81
	v_max_f32_e32 v239, v80, v80
	v_max_f32_e32 v238, v239, v238
	v_max3_f32 v238, v238, v82, v83
	v_max3_f32 v238, v238, v84, v85
	v_max3_f32 v238, v238, v86, v87
	v_mfma_f32_32x32x16_bf16 v[48:63], v[204:207], v[220:223], v[48:63]
	ds_read_b64_tr_b16 v[220:221], v180 offset:0x1200
	ds_read_b64_tr_b16 v[222:223], v180 offset:0x1a00
	v_max3_f32 v238, v238, v88, v89
	v_max3_f32 v238, v238, v90, v91
	v_max3_f32 v238, v238, v92, v93
	v_max3_f32 v238, v238, v94, v95
	v_max3_f32 v238, v238, v64, v65
	v_max3_f32 v238, v238, v66, v67
	v_mfma_f32_32x32x16_bf16 v[48:63], v[144:147], v[224:227], v[48:63]
	ds_read_b64_tr_b16 v[224:225], v180 offset:0x2200
	ds_read_b64_tr_b16 v[226:227], v180 offset:0x2a00
	v_max3_f32 v238, v238, v68, v69
	v_max3_f32 v238, v238, v70, v71
	v_max3_f32 v238, v238, v72, v73
	v_max3_f32 v238, v238, v74, v75
	v_max3_f32 v238, v238, v76, v77
	v_max3_f32 v238, v238, v78, v79
	v_mfma_f32_32x32x16_bf16 v[48:63], v[148:151], v[228:231], v[48:63]
	ds_read_b64_tr_b16 v[228:229], v180 offset:0x3200
	ds_read_b64_tr_b16 v[230:231], v180 offset:0x3a00
	v_mov_b32_e32 v239, v238
	s_nop 1
	v_permlane32_swap_b32_e32 v238, v239
	v_max_f32_e32 v239, v239, v239
	v_max_f32_e32 v238, v238, v238
	v_max_f32_e32 v238, v238, v239
	s_waitcnt lgkmcnt(6)
; #define SWRITE(b, i) do { *(bf16x8*)(V_lds + (b) * SHM_V + vst0) = sr_[i].vs0; *(bf16x8*)(V_lds + (b) * SHM_V + vst1) = sr_[i].vs1; \
;     _Pragma("unroll") for (int c_ = 0; c_ < KCH; ++c_) *(bf16x8*)(K_lds + (b) * SHM_K + kwo[c_]) = sr_[i].ks[c_]; } while (0)
; #define RESC(al) do { if (__any((al) < 1.f)) { if (hi == 0) al_l[r32] = (al); asm volatile("s_waitcnt lgkmcnt(0)" ::: "memory"); \
;     _Pragma("unroll") for (int d = 0; d < 4; ++d) _Pragma("unroll") for (int r = 0; r < 16; ++r) o[d][r] *= al_l[crow(r, hi)]; } } while (0)
; template <int DQK, int DK1, int LDQ, int LDK, int LDKR, int LDV, int NQL, int SDEPTH>
; __device__ __forceinline__ void attn_core(const AttnArgs& a, char* lds, f32x16 (&o)[4]) {
;     ...
;         pv_d0(o, vb0, pa0, pa1, pa2, pa3); partialSM(pB0, pB1, m_reg, mnB, alB, a.C, a.thr);
;         __syncthreads(); SWRITE(0, SE);
;         RESC(alB); __syncthreads();
	v_mfma_f32_32x32x16_bf16 v[32:47], v[138:141], v[216:219], v[32:47]
	ds_read_b64_tr_b16 v[216:217], v180 offset:0x400
	ds_read_b64_tr_b16 v[218:219], v180 offset:0xc00
	v_sub_f32_e32 v239, v238, v142
	v_cmp_ge_f32_e32 vcc, s76, v239
	v_max_f32_e32 v239, v142, v142
	v_max_f32_e32 v238, v239, v238
	v_sub_f32_e32 v239, v142, v238
	v_mul_f32_e32 v239, 0x3e38aa3b, v239
	s_waitcnt lgkmcnt(6)
	v_mfma_f32_32x32x16_bf16 v[32:47], v[204:207], v[220:223], v[32:47]
	ds_read_b64_tr_b16 v[220:221], v180 offset:0x1400
	ds_read_b64_tr_b16 v[222:223], v180 offset:0x1c00
	v_exp_f32_e32 v239, v239
	s_cmp_eq_u64 vcc, exec
	s_cselect_b64 s[14:15], -1, 0
	v_cndmask_b32_e64 v200, v239, 1.0, s[14:15]
	v_cmp_gt_f32_e32 vcc, 1.0, v200
	s_waitcnt lgkmcnt(6)
	v_mfma_f32_32x32x16_bf16 v[32:47], v[144:147], v[224:227], v[32:47]
	ds_read_b64_tr_b16 v[224:225], v180 offset:0x2400
	ds_read_b64_tr_b16 v[226:227], v180 offset:0x2c00
	v_cndmask_b32_e64 v241, v238, v142, s[14:15]
	v_mul_f32_e32 v239, 0xbe38aa3b, v241
	v_fmamk_f32 v80, v80, 0x3e38aa3b, v239
	v_fmamk_f32 v81, v81, 0x3e38aa3b, v239
	s_waitcnt lgkmcnt(6)
	v_mfma_f32_32x32x16_bf16 v[32:47], v[148:151], v[228:231], v[32:47]
	ds_read_b64_tr_b16 v[228:229], v180 offset:0x3400
	ds_read_b64_tr_b16 v[230:231], v180 offset:0x3c00
	v_fmamk_f32 v82, v82, 0x3e38aa3b, v239
	v_fmamk_f32 v83, v83, 0x3e38aa3b, v239
	v_fmamk_f32 v84, v84, 0x3e38aa3b, v239
	v_fmamk_f32 v85, v85, 0x3e38aa3b, v239
	s_waitcnt lgkmcnt(6)
	v_mfma_f32_32x32x16_bf16 v[16:31], v[138:141], v[216:219], v[16:31]
	ds_read_b64_tr_b16 v[216:217], v180 offset:0x600
	ds_read_b64_tr_b16 v[218:219], v180 offset:0xe00
	v_fmamk_f32 v86, v86, 0x3e38aa3b, v239
	v_fmamk_f32 v87, v87, 0x3e38aa3b, v239
	v_fmamk_f32 v88, v88, 0x3e38aa3b, v239
	v_fmamk_f32 v89, v89, 0x3e38aa3b, v239
	s_waitcnt lgkmcnt(6)
	v_mfma_f32_32x32x16_bf16 v[16:31], v[204:207], v[220:223], v[16:31]
	ds_read_b64_tr_b16 v[220:221], v180 offset:0x1600
	ds_read_b64_tr_b16 v[222:223], v180 offset:0x1e00
	v_fmamk_f32 v90, v90, 0x3e38aa3b, v239
	v_fmamk_f32 v91, v91, 0x3e38aa3b, v239
	v_fmamk_f32 v92, v92, 0x3e38aa3b, v239
	v_fmamk_f32 v93, v93, 0x3e38aa3b, v239
	s_waitcnt lgkmcnt(6)
	v_mfma_f32_32x32x16_bf16 v[16:31], v[144:147], v[224:227], v[16:31]
	ds_read_b64_tr_b16 v[224:225], v180 offset:0x2600
	ds_read_b64_tr_b16 v[226:227], v180 offset:0x2e00
	v_fmamk_f32 v94, v94, 0x3e38aa3b, v239
	v_fmamk_f32 v95, v95, 0x3e38aa3b, v239
	s_waitcnt lgkmcnt(6)
	v_mfma_f32_32x32x16_bf16 v[16:31], v[148:151], v[228:231], v[16:31]
	ds_read_b64_tr_b16 v[228:229], v180 offset:0x3600
	ds_read_b64_tr_b16 v[230:231], v180 offset:0x3e00
	v_exp_f32_e32 v153, v81
	v_exp_f32_e32 v152, v83
	v_exp_f32_e32 v142, v88
	v_exp_f32_e32 v143, v90
	s_waitcnt lgkmcnt(6)
	v_mfma_f32_32x32x16_bf16 v[0:15], v[138:141], v[216:219], v[0:15]
	s_waitcnt lgkmcnt(4)
	v_mfma_f32_32x32x16_bf16 v[0:15], v[204:207], v[220:223], v[0:15]
	v_exp_f32_e32 v138, v80
	s_waitcnt lgkmcnt(2)
	v_mfma_f32_32x32x16_bf16 v[0:15], v[144:147], v[224:227], v[0:15]
	v_exp_f32_e32 v144, v92
	v_exp_f32_e32 v147, v93
	v_exp_f32_e32 v145, v94
	v_exp_f32_e32 v146, v95
	v_exp_f32_e32 v139, v82
	s_waitcnt lgkmcnt(0)
	v_mfma_f32_32x32x16_bf16 v[0:15], v[148:151], v[228:231], v[0:15]
	v_exp_f32_e32 v140, v84
	v_exp_f32_e32 v141, v86
	s_barrier
	s_waitcnt vmcnt(5)
	ds_write_b128 v181, v[114:117]
	s_waitcnt vmcnt(4)
	ds_write_b128 v184, v[118:121]
	s_waitcnt vmcnt(3)
	ds_write_b128 v182, v[122:125] offset:32768
	s_cbranch_vccz .LBB0_175
	s_and_saveexec_b64 s[38:39], s[12:13]
	ds_write_b32 v177, v200 offset:49280
	s_or_b64 exec, exec, s[38:39]
	s_waitcnt lgkmcnt(0)
	v_add_u32_e32 v242, v161, v96
	ds_read_b128 v[244:247], v242 offset:49376
	ds_read_b128 v[148:151], v242 offset:49344
	ds_read_b128 v[204:207], v242 offset:49312
	ds_read_b128 v[216:219], v242 offset:49280
	s_waitcnt lgkmcnt(3)
	v_pk_mul_f32 v[60:61], v[60:61], v[244:245]
	s_waitcnt lgkmcnt(2)
	v_pk_mul_f32 v[56:57], v[56:57], v[148:149]
	s_waitcnt lgkmcnt(1)
	v_pk_mul_f32 v[52:53], v[52:53], v[204:205]
	v_pk_mul_f32 v[62:63], v[62:63], v[246:247]
	v_pk_mul_f32 v[58:59], v[58:59], v[150:151]
	v_pk_mul_f32 v[54:55], v[54:55], v[206:207]
	s_waitcnt lgkmcnt(0)
	v_pk_mul_f32 v[50:51], v[50:51], v[218:219]
	v_pk_mul_f32 v[48:49], v[48:49], v[216:217]
	v_pk_mul_f32 v[44:45], v[44:45], v[244:245]
	v_pk_mul_f32 v[40:41], v[40:41], v[148:149]
	v_pk_mul_f32 v[36:37], v[36:37], v[204:205]
	v_pk_mul_f32 v[46:47], v[46:47], v[246:247]
	v_pk_mul_f32 v[42:43], v[42:43], v[150:151]
	v_pk_mul_f32 v[38:39], v[38:39], v[206:207]
	v_pk_mul_f32 v[34:35], v[34:35], v[218:219]
	v_pk_mul_f32 v[32:33], v[32:33], v[216:217]
	v_pk_mul_f32 v[28:29], v[28:29], v[244:245]
	v_pk_mul_f32 v[24:25], v[24:25], v[148:149]
	v_pk_mul_f32 v[20:21], v[20:21], v[204:205]
	v_pk_mul_f32 v[30:31], v[30:31], v[246:247]
	v_pk_mul_f32 v[26:27], v[26:27], v[150:151]
	v_pk_mul_f32 v[22:23], v[22:23], v[206:207]
	v_pk_mul_f32 v[18:19], v[18:19], v[218:219]
	v_pk_mul_f32 v[16:17], v[16:17], v[216:217]
	v_pk_mul_f32 v[12:13], v[12:13], v[244:245]
	v_pk_mul_f32 v[8:9], v[8:9], v[148:149]
	v_pk_mul_f32 v[4:5], v[4:5], v[204:205]
	v_pk_mul_f32 v[14:15], v[14:15], v[246:247]
	v_pk_mul_f32 v[10:11], v[10:11], v[150:151]
	v_pk_mul_f32 v[6:7], v[6:7], v[206:207]
	v_pk_mul_f32 v[2:3], v[2:3], v[218:219]
	v_pk_mul_f32 v[0:1], v[0:1], v[216:217]

; __device__ __forceinline__ void partialSM(f32x16& p0, f32x16& p1, float& m_reg, float& mn, float& alpha, const float C, const float thr) {
;     ...
;     else { mn = fmaxf(m_reg, pmax); alpha = __builtin_amdgcn_exp2f((m_reg - mn) * C); m_reg = mn; }
;     const float mnC = -mn * C;
; #pragma unroll
;     for (int r = 0; r < 16; ++r) p0[r] = fmaf(p0[r], C, mnC);
; #pragma unroll
;     for (int r = 0; r < 16; ++r) p1[r] = fmaf(p1[r], C, mnC);
; #pragma unroll
;     for (int r = 0; r < 16; ++r) p0[r] = __builtin_amdgcn_exp2f(p0[r]);
; }
; __device__ __forceinline__ void finishSM(f32x16& p0, f32x16& p1, float alpha, float& l_reg, bf16x8& pa0, bf16x8& pa1, bf16x8& pa2, bf16x8& pa3) {
; #pragma unroll
;     for (int r = 0; r < 16; ++r) p1[r] = __builtin_amdgcn_exp2f(p1[r]);
;     float ps = 0;
; #pragma unroll
;     for (int r = 0; r < 16; ++r) ps += p0[r];
; #pragma unroll
;     for (int r = 0; r < 16; ++r) ps += p1[r];
;     { auto rr = __builtin_amdgcn_permlane32_swap(__float_as_uint(ps), __float_as_uint(ps), false, false);
;       ps = __uint_as_float(rr[0]) + __uint_as_float(rr[1]); }
;     l_reg = l_reg * alpha + ps;
; template <int DQK, int DK1, int LDQ, int LDK, int LDKR, int LDV, int NQL, int SDEPTH>
; __device__ __forceinline__ void attn_core(const AttnArgs& a, char* lds, f32x16 (&o)[4]) {
;     ...
;     for (int j = 1; j + 1 < NT; j += 2) {
.LBB0_181:
	v_mov_b32_e32 v142, v241
	v_mul_f32_e32 v132, 0xbe38aa3b, v142
	v_mov_b32_e32 v133, v132
	v_fmac_f32_e32 v133, 0x3e38aa3b, v95
	v_exp_f32_e32 v153, v84
	v_exp_f32_e32 v152, v86
	v_exp_f32_e32 v151, v89
	v_exp_f32_e32 v150, v91
	v_exp_f32_e32 v146, v133
	v_pk_fma_f32 v[138:139], v[64:65], s[8:9], v[132:133] op_sel_hi:[1,0,0]
	v_add_f32_e32 v64, v196, v198
	v_fmac_f32_e32 v64, v194, v178
	v_add_f32_e32 v178, v204, v206
	s_add_i32 s52, s52, 2
	v_pk_fma_f32 v[136:137], v[66:67], s[8:9], v[132:133] op_sel_hi:[1,0,0]
	v_pk_fma_f32 v[130:131], v[68:69], s[8:9], v[132:133] op_sel_hi:[1,0,0]
	v_pk_fma_f32 v[128:129], v[70:71], s[8:9], v[132:133] op_sel_hi:[1,0,0]
	v_pk_fma_f32 v[126:127], v[72:73], s[8:9], v[132:133] op_sel_hi:[1,0,0]
	v_pk_fma_f32 v[140:141], v[74:75], s[8:9], v[132:133] op_sel_hi:[1,0,0]
	v_pk_fma_f32 v[134:135], v[76:77], s[8:9], v[132:133] op_sel_hi:[1,0,0]
	v_pk_fma_f32 v[132:133], v[78:79], s[8:9], v[132:133] op_sel_hi:[1,0,0]
	v_fmac_f32_e32 v178, v64, v200
	s_cmp_gt_u32 s37, 32
	s_waitcnt lgkmcnt(0)
	s_cbranch_scc1 .Lrot_x171
	v_mov_b32_e32 v194, v143
	s_add_i32 s37, s52, -3
	s_branch .LBB0_171
.Lrot_x171:
	s_barrier

; __device__ __forceinline__ void finishSM(f32x16& p0, f32x16& p1, float alpha, float& l_reg, bf16x8& pa0, bf16x8& pa1, bf16x8& pa2, bf16x8& pa3) {
; #pragma unroll
;     for (int r = 0; r < 16; ++r) p1[r] = __builtin_amdgcn_exp2f(p1[r]);
;     float ps = 0;
; #pragma unroll
;     for (int r = 0; r < 16; ++r) ps += p0[r];
; #pragma unroll
;     for (int r = 0; r < 16; ++r) ps += p1[r];
;     { auto rr = __builtin_amdgcn_permlane32_swap(__float_as_uint(ps), __float_as_uint(ps), false, false);
;       ps = __uint_as_float(rr[0]) + __uint_as_float(rr[1]); }
;     l_reg = l_reg * alpha + ps;
.LBB0_219:
	s_barrier
	ds_read_b128 v[64:67], v184 offset:57344
	ds_read_b128 v[68:71], v216 offset:12288
	ds_read_b128 v[222:225], v192 offset:57344
	ds_read_b128 v[226:229], v208 offset:12288
	v_exp_f32_e32 v207, v130
	v_add_f32_e32 v130, 0, v219
	s_waitcnt lgkmcnt(3)
	v_mfma_f32_32x32x16_bf16 v[80:95], v[64:67], v[126:129], 0
	v_add_f32_e32 v130, v221, v130
	v_add_f32_e32 v130, v157, v130
	v_add_f32_e32 v130, v220, v130
	v_add_f32_e32 v130, v156, v130
	v_add_f32_e32 v130, v218, v130
	v_add_f32_e32 v130, v154, v130
	v_add_f32_e32 v130, v155, v130
	s_waitcnt lgkmcnt(2)
	v_mfma_f32_32x32x16_bf16 v[64:79], v[68:71], v[126:129], 0
	v_add_f32_e32 v130, v151, v130
	v_add_f32_e32 v130, v153, v130
	v_add_f32_e32 v130, v150, v130
	v_add_f32_e32 v130, v152, v130
	v_exp_f32_e32 v142, v142
	v_add_f32_e32 v130, v147, v130
	v_exp_f32_e32 v143, v143
	s_waitcnt lgkmcnt(1)
	v_mfma_f32_32x32x16_bf16 v[80:95], v[222:225], v[122:125], v[80:95]
	v_add_f32_e32 v130, v149, v130
	v_exp_f32_e32 v140, v140
	v_add_f32_e32 v130, v146, v130
	v_exp_f32_e32 v141, v141
	v_add_f32_e32 v130, v148, v130
	v_exp_f32_e32 v134, v134
	v_add_f32_e32 v130, v142, v130
	s_waitcnt lgkmcnt(0)
	v_mfma_f32_32x32x16_bf16 v[64:79], v[226:229], v[122:125], v[64:79]
	ds_read_b128 v[222:225], v190 offset:57344
	ds_read_b128 v[226:229], v206 offset:12288
	v_exp_f32_e32 v135, v135
	v_add_f32_e32 v130, v143, v130
	v_exp_f32_e32 v191, v132
	v_add_f32_e32 v130, v140, v130
	v_exp_f32_e32 v205, v133
	v_add_f32_e32 v130, v141, v130
	s_waitcnt lgkmcnt(1)
	v_mfma_f32_32x32x16_bf16 v[80:95], v[222:225], v[118:121], v[80:95]
	v_add_f32_e32 v130, v134, v130
	v_exp_f32_e32 v210, v131
	v_add_f32_e32 v130, v135, v130
	v_exp_f32_e32 v144, v144
	v_add_f32_e32 v130, v191, v130
	v_exp_f32_e32 v145, v145
	v_add_f32_e32 v130, v205, v130
	s_waitcnt lgkmcnt(0)
	v_mfma_f32_32x32x16_bf16 v[64:79], v[226:229], v[118:121], v[64:79]
	ds_read_b128 v[222:225], v173 offset:57344
	ds_read_b128 v[226:229], v202 offset:12288
	v_exp_f32_e32 v138, v138
	v_add_f32_e32 v130, v207, v130
	v_exp_f32_e32 v139, v139
	v_add_f32_e32 v130, v210, v130
	v_exp_f32_e32 v136, v136
	v_add_f32_e32 v130, v144, v130
	s_waitcnt lgkmcnt(1)
	v_mfma_f32_32x32x16_bf16 v[80:95], v[222:225], v[114:117], v[80:95]
	v_exp_f32_e32 v137, v137
	v_add_f32_e32 v130, v145, v130
	v_add_f32_e32 v130, v138, v130
	v_add_f32_e32 v130, v139, v130
	v_add_f32_e32 v130, v136, v130
	s_waitcnt lgkmcnt(0)
	v_mfma_f32_32x32x16_bf16 v[64:79], v[226:229], v[114:117], v[64:79]
	ds_read_b128 v[222:225], v184 offset:57472
	ds_read_b128 v[226:229], v216 offset:12416
	s_waitcnt lgkmcnt(1)
	v_mfma_f32_32x32x16_bf16 v[80:95], v[222:225], v[110:113], v[80:95]
	s_waitcnt lgkmcnt(0)
	v_mfma_f32_32x32x16_bf16 v[64:79], v[226:229], v[110:113], v[64:79]
	ds_read_b128 v[222:225], v192 offset:57472
	ds_read_b128 v[226:229], v208 offset:12416
	s_waitcnt lgkmcnt(1)
	v_mfma_f32_32x32x16_bf16 v[80:95], v[222:225], v[106:109], v[80:95]
	s_waitcnt lgkmcnt(0)
	v_mfma_f32_32x32x16_bf16 v[64:79], v[226:229], v[106:109], v[64:79]
	ds_read_b128 v[222:225], v190 offset:57472
	ds_read_b128 v[226:229], v206 offset:12416
	s_waitcnt lgkmcnt(1)
	v_mfma_f32_32x32x16_bf16 v[80:95], v[222:225], v[102:105], v[80:95]
	s_waitcnt lgkmcnt(0)
	v_mfma_f32_32x32x16_bf16 v[64:79], v[226:229], v[102:105], v[64:79]
	ds_read_b128 v[222:225], v173 offset:57472
	ds_read_b128 v[226:229], v202 offset:12416
	s_waitcnt lgkmcnt(1)
	v_mfma_f32_32x32x16_bf16 v[80:95], v[222:225], v[98:101], v[80:95]
	s_waitcnt lgkmcnt(0)
	v_mfma_f32_32x32x16_bf16 v[64:79], v[226:229], v[98:101], v[64:79]
	ds_read_b128 v[222:225], v184 offset:57600
	ds_read_b128 v[226:229], v216 offset:12544
	ds_read_b128 v[230:233], v181
	s_waitcnt lgkmcnt(0)
	v_mfma_f32_32x32x16_bf16 v[80:95], v[222:225], v[230:233], v[80:95]
	v_mfma_f32_32x32x16_bf16 v[64:79], v[226:229], v[230:233], v[64:79]
	ds_read_b128 v[222:225], v192 offset:57600
	ds_read_b128 v[226:229], v208 offset:12544
	ds_read_b128 v[230:233], v181 offset:8192
	s_waitcnt lgkmcnt(0)
	v_mfma_f32_32x32x16_bf16 v[80:95], v[222:225], v[230:233], v[80:95]
	v_mfma_f32_32x32x16_bf16 v[64:79], v[226:229], v[230:233], v[64:79]
	ds_read_b128 v[222:225], v190 offset:57600
	ds_read_b128 v[226:229], v206 offset:12544
	ds_read_b128 v[230:233], v181 offset:16384
	s_waitcnt lgkmcnt(0)
	v_mfma_f32_32x32x16_bf16 v[80:95], v[222:225], v[230:233], v[80:95]
	v_mfma_f32_32x32x16_bf16 v[64:79], v[226:229], v[230:233], v[64:79]
	ds_read_b128 v[222:225], v173 offset:57600
	ds_read_b128 v[226:229], v202 offset:12544
	ds_read_b128 v[230:233], v181 offset:24576
	s_waitcnt lgkmcnt(0)
; #define SBAR() __builtin_amdgcn_sched_barrier(0)
; template <int OFF> __device__ __forceinline__ s16x4 tr_read(int vb) { s16x4 r; asm volatile("ds_read_b64_tr_b16 %0, %1 offset:%2" : "=&v"(r) : "v"(vb), "i"(OFF) : "memory"); return r; }
; template <int D0> __device__ __forceinline__ void pv_one(f32x16& od, int vb, bf16x8 pa0, bf16x8 pa1, bf16x8 pa2, bf16x8 pa3) {
;     const s16x4 l0 = tr_read<v_rd_off(D0, 0, 0)>(vb), h0 = tr_read<v_rd_off(D0, 0, 1)>(vb), l1 = tr_read<v_rd_off(D0, 1, 0)>(vb), h1 = tr_read<v_rd_off(D0, 1, 1)>(vb);
;     const s16x4 l2 = tr_read<v_rd_off(D0, 2, 0)>(vb), h2 = tr_read<v_rd_off(D0, 2, 1)>(vb), l3 = tr_read<v_rd_off(D0, 3, 0)>(vb), h3 = tr_read<v_rd_off(D0, 3, 1)>(vb);
;     asm volatile("s_waitcnt lgkmcnt(0)" ::: "memory"); SBAR();
;     ...
;     od = __builtin_amdgcn_mfma_f32_32x32x16_bf16(pa0, PK(l0, h0), od, 0, 0, 0);
;     od = __builtin_amdgcn_mfma_f32_32x32x16_bf16(pa1, PK(l1, h1), od, 0, 0, 0);
;     od = __builtin_amdgcn_mfma_f32_32x32x16_bf16(pa2, PK(l2, h2), od, 0, 0, 0);
;     od = __builtin_amdgcn_mfma_f32_32x32x16_bf16(pa3, PK(l3, h3), od, 0, 0, 0);
;     ...
; }
; __device__ __forceinline__ void pv_d0(f32x16* o, int vb, bf16x8 pa0, bf16x8 pa1, bf16x8 pa2, bf16x8 pa3) {
;     pv_one<0>(o[0], vb, pa0, pa1, pa2, pa3); pv_one<1>(o[1], vb, pa0, pa1, pa2, pa3); pv_one<2>(o[2], vb, pa0, pa1, pa2, pa3); pv_one<3>(o[3], vb, pa0, pa1, pa2, pa3);
; __device__ __forceinline__ void finishSM(f32x16& p0, f32x16& p1, float alpha, float& l_reg, bf16x8& pa0, bf16x8& pa1, bf16x8& pa2, bf16x8& pa3) {
; #pragma unroll
;     for (int r = 0; r < 16; ++r) p1[r] = __builtin_amdgcn_exp2f(p1[r]);
;     float ps = 0;
; #pragma unroll
;     for (int r = 0; r < 16; ++r) ps += p0[r];
; #pragma unroll
;     for (int r = 0; r < 16; ++r) ps += p1[r];
;     { auto rr = __builtin_amdgcn_permlane32_swap(__float_as_uint(ps), __float_as_uint(ps), false, false);
;       ps = __uint_as_float(rr[0]) + __uint_as_float(rr[1]); }
;     l_reg = l_reg * alpha + ps;
;     ...
;     PK4(p0, 0, pa0); PK4(p0, 8, pa1); PK4(p1, 0, pa2); PK4(p1, 8, pa3);
;     ...
; }
	v_mfma_f32_32x32x16_bf16 v[80:95], v[222:225], v[230:233], v[80:95]
	v_add_f32_e32 v222, v137, v130
	v_mov_b32_e32 v223, v222
	v_cvt_pk_bf16_f32 v130, v219, v221
	v_cvt_pk_bf16_f32 v131, v157, v220
	v_cvt_pk_bf16_f32 v132, v156, v218
	v_cvt_pk_bf16_f32 v133, v154, v155
	v_cvt_pk_bf16_f32 v154, v151, v153
	v_mfma_f32_32x32x16_bf16 v[64:79], v[226:229], v[230:233], v[64:79]
	v_cvt_pk_bf16_f32 v155, v150, v152
	v_cvt_pk_bf16_f32 v156, v147, v149
	v_cvt_pk_bf16_f32 v157, v146, v148
	v_cvt_pk_bf16_f32 v218, v142, v143
	v_cvt_pk_bf16_f32 v219, v140, v141
	v_cvt_pk_bf16_f32 v220, v134, v135
	v_cvt_pk_bf16_f32 v221, v191, v205
	v_cvt_pk_bf16_f32 v224, v207, v210
	v_cvt_pk_bf16_f32 v225, v144, v145
	v_cvt_pk_bf16_f32 v226, v138, v139
	v_cvt_pk_bf16_f32 v227, v136, v137
	s_nop 0
	v_permlane32_swap_b32_e32 v222, v223
	v_permlane32_swap_b32_e32 v130, v132
	v_permlane32_swap_b32_e32 v225, v227
	v_permlane32_swap_b32_e32 v131, v133
	v_permlane32_swap_b32_e32 v154, v156
	v_permlane32_swap_b32_e32 v155, v157
	v_permlane32_swap_b32_e32 v218, v220
	v_permlane32_swap_b32_e32 v219, v221
	v_permlane32_swap_b32_e32 v224, v226
	s_cmp_lt_u32 s69, s68
	s_cselect_b32 s14, 0, s68
	s_cselect_b32 s15, s25, s28
	s_lshl_b32 s14, s14, 6
	s_sub_i32 s14, s15, s14
	s_add_i32 s14, s37, s14
	s_ashr_i32 s15, s14, 31
	v_lshl_add_u64 v[134:135], s[14:15], 0, v[174:175]
	v_lshl_add_u64 v[136:137], v[176:177], 0, s[14:15]
	v_lshlrev_b64 v[134:135], 12, v[134:135]
	v_lshlrev_b64 v[136:137], 12, v[136:137]
	v_lshl_add_u64 v[134:135], v[178:179], 0, v[134:135]
	v_lshl_add_u64 v[138:139], v[178:179], 0, v[136:137]
	v_mad_i64_i32 v[142:143], s[20:21], v164, s14, 0
	v_mad_i64_i32 v[146:147], s[20:21], v168, s14, 0
	v_mad_i64_i32 v[150:151], s[14:15], v172, s14, 0
	global_load_dwordx4 v[134:137], v[134:135], off offset:256
	s_nop 0
	global_load_dwordx4 v[138:141], v[138:139], off offset:256
	v_lshl_add_u64 v[142:143], v[142:143], 1, v[162:163]
	v_lshl_add_u64 v[146:147], v[146:147], 1, v[166:167]
	v_lshl_add_u64 v[150:151], v[150:151], 1, v[170:171]
	global_load_dwordx4 v[142:145], v[142:143], off
	s_nop 0
	global_load_dwordx4 v[146:149], v[146:147], off
	s_nop 0
	global_load_dwordx4 v[150:153], v[150:151], off
	ds_read_b64_tr_b16 v[228:229], v200 offset:0
	ds_read_b64_tr_b16 v[230:231], v200 offset:0x800
	ds_read_b64_tr_b16 v[232:233], v200 offset:0x1000
	ds_read_b64_tr_b16 v[234:235], v200 offset:0x1800
	ds_read_b64_tr_b16 v[236:237], v200 offset:0x2000
	ds_read_b64_tr_b16 v[238:239], v200 offset:0x2800
	ds_read_b64_tr_b16 v[240:241], v200 offset:0x3000
	ds_read_b64_tr_b16 v[242:243], v200 offset:0x3800
	s_waitcnt lgkmcnt(0)
	s_nop 0
	v_mfma_f32_32x32x16_bf16 v[48:63], v[130:133], v[228:231], v[48:63]
	ds_read_b64_tr_b16 v[228:229], v200 offset:0x200
	ds_read_b64_tr_b16 v[230:231], v200 offset:0xa00
	v_mfma_f32_32x32x16_bf16 v[48:63], v[154:157], v[232:235], v[48:63]
	ds_read_b64_tr_b16 v[232:233], v200 offset:0x1200
	ds_read_b64_tr_b16 v[234:235], v200 offset:0x1a00
	v_mfma_f32_32x32x16_bf16 v[48:63], v[218:221], v[236:239], v[48:63]
	ds_read_b64_tr_b16 v[236:237], v200 offset:0x2200
	ds_read_b64_tr_b16 v[238:239], v200 offset:0x2a00
	v_mfma_f32_32x32x16_bf16 v[48:63], v[224:227], v[240:243], v[48:63]
	ds_read_b64_tr_b16 v[240:241], v200 offset:0x3200
	ds_read_b64_tr_b16 v[242:243], v200 offset:0x3a00
	s_waitcnt lgkmcnt(6)
	v_mfma_f32_32x32x16_bf16 v[32:47], v[130:133], v[228:231], v[32:47]
	ds_read_b64_tr_b16 v[228:229], v200 offset:0x400
	ds_read_b64_tr_b16 v[230:231], v200 offset:0xc00
	s_waitcnt lgkmcnt(6)
	v_mfma_f32_32x32x16_bf16 v[32:47], v[154:157], v[232:235], v[32:47]
	ds_read_b64_tr_b16 v[232:233], v200 offset:0x1400
	ds_read_b64_tr_b16 v[234:235], v200 offset:0x1c00
	s_waitcnt lgkmcnt(6)
	v_mfma_f32_32x32x16_bf16 v[32:47], v[218:221], v[236:239], v[32:47]
	ds_read_b64_tr_b16 v[236:237], v200 offset:0x2400
	ds_read_b64_tr_b16 v[238:239], v200 offset:0x2c00
	s_waitcnt lgkmcnt(6)
	v_mfma_f32_32x32x16_bf16 v[32:47], v[224:227], v[240:243], v[32:47]
	ds_read_b64_tr_b16 v[240:241], v200 offset:0x3400
	ds_read_b64_tr_b16 v[242:243], v200 offset:0x3c00
	s_waitcnt lgkmcnt(6)
	v_mfma_f32_32x32x16_bf16 v[16:31], v[130:133], v[228:231], v[16:31]
	ds_read_b64_tr_b16 v[228:229], v200 offset:0x600
	ds_read_b64_tr_b16 v[230:231], v200 offset:0xe00
	s_waitcnt lgkmcnt(6)
	v_mfma_f32_32x32x16_bf16 v[16:31], v[154:157], v[232:235], v[16:31]
	ds_read_b64_tr_b16 v[232:233], v200 offset:0x1600
	ds_read_b64_tr_b16 v[234:235], v200 offset:0x1e00
	s_waitcnt lgkmcnt(6)
	v_mfma_f32_32x32x16_bf16 v[16:31], v[218:221], v[236:239], v[16:31]
	ds_read_b64_tr_b16 v[236:237], v200 offset:0x2600
	ds_read_b64_tr_b16 v[238:239], v200 offset:0x2e00
	s_waitcnt lgkmcnt(6)
	v_mfma_f32_32x32x16_bf16 v[16:31], v[224:227], v[240:243], v[16:31]
	ds_read_b64_tr_b16 v[240:241], v200 offset:0x3600
	ds_read_b64_tr_b16 v[242:243], v200 offset:0x3e00
	s_waitcnt lgkmcnt(6)
	v_mfma_f32_32x32x16_bf16 v[0:15], v[130:133], v[228:231], v[0:15]
	v_max_f32_e32 v130, v81, v81
	v_max_f32_e32 v131, v80, v80
	v_max_f32_e32 v130, v131, v130
	v_max3_f32 v130, v130, v82, v83
	v_max3_f32 v130, v130, v84, v85
	v_max3_f32 v130, v130, v86, v87
	v_max3_f32 v130, v130, v88, v89
	v_max3_f32 v130, v130, v90, v91
	v_max3_f32 v130, v130, v92, v93
	s_waitcnt lgkmcnt(4)
	v_mfma_f32_32x32x16_bf16 v[0:15], v[154:157], v[232:235], v[0:15]
	v_max3_f32 v130, v130, v94, v95
	v_max3_f32 v130, v130, v64, v65
	v_max3_f32 v130, v130, v66, v67
	v_max3_f32 v130, v130, v68, v69
	v_max3_f32 v130, v130, v70, v71
	v_max3_f32 v130, v130, v72, v73
	v_max3_f32 v130, v130, v74, v75
	v_max3_f32 v130, v130, v76, v77
	s_waitcnt lgkmcnt(2)
	v_mfma_f32_32x32x16_bf16 v[0:15], v[218:221], v[236:239], v[0:15]
	v_max3_f32 v130, v130, v78, v79
	v_mov_b32_e32 v131, v130
	s_nop 1
	v_permlane32_swap_b32_e32 v130, v131
	v_max_f32_e32 v131, v131, v131
	v_max_f32_e32 v130, v130, v130
	v_max_f32_e32 v130, v130, v131
	v_sub_f32_e32 v131, v130, v204
	v_cmp_ge_f32_e32 vcc, s72, v131
	v_max_f32_e32 v131, v204, v204
	v_max_f32_e32 v130, v131, v130
	s_waitcnt lgkmcnt(0)
	v_mfma_f32_32x32x16_bf16 v[0:15], v[224:227], v[240:243], v[0:15]
	v_sub_f32_e32 v131, v204, v130
	v_mul_f32_e32 v131, 0x3dd53b94, v131
	v_exp_f32_e32 v131, v131
	s_cmp_eq_u64 vcc, exec
	s_cselect_b64 s[14:15], -1, 0
	v_cndmask_b32_e64 v225, v131, 1.0, s[14:15]
	v_cmp_gt_f32_e32 vcc, 1.0, v225
	s_barrier
	s_waitcnt vmcnt(4)
	ds_write_b128 v186, v[134:137]
	s_waitcnt vmcnt(3)
	ds_write_b128 v188, v[138:141]
	s_waitcnt vmcnt(2)
	ds_write_b128 v194, v[142:145] offset:32768
	s_waitcnt vmcnt(1)
	ds_write_b128 v196, v[146:149] offset:32768
	s_waitcnt vmcnt(0)
	ds_write_b128 v198, v[150:153] offset:32768
	s_cbranch_vccz .LBB0_223
	s_and_saveexec_b64 s[20:21], s[12:13]
	ds_write_b32 v165, v225 offset:128
	s_or_b64 exec, exec, s[20:21]
	s_waitcnt lgkmcnt(0)
	v_add_u32_e32 v131, v161, v96
	ds_read_b128 v[132:135], v131 offset:224
	ds_read_b128 v[136:139], v131 offset:192
	ds_read_b128 v[140:143], v131 offset:160
	ds_read_b128 v[144:147], v131 offset:128
	s_waitcnt lgkmcnt(3)
	v_pk_mul_f32 v[60:61], v[60:61], v[132:133]
	s_waitcnt lgkmcnt(2)
	v_pk_mul_f32 v[56:57], v[56:57], v[136:137]
	s_waitcnt lgkmcnt(1)
	v_pk_mul_f32 v[52:53], v[52:53], v[140:141]
	v_pk_mul_f32 v[62:63], v[62:63], v[134:135]
	v_pk_mul_f32 v[58:59], v[58:59], v[138:139]
	v_pk_mul_f32 v[54:55], v[54:55], v[142:143]
	s_waitcnt lgkmcnt(0)
	v_pk_mul_f32 v[50:51], v[50:51], v[146:147]
	v_pk_mul_f32 v[48:49], v[48:49], v[144:145]
	v_pk_mul_f32 v[44:45], v[44:45], v[132:133]
	v_pk_mul_f32 v[40:41], v[40:41], v[136:137]
	v_pk_mul_f32 v[36:37], v[36:37], v[140:141]
	v_pk_mul_f32 v[46:47], v[46:47], v[134:135]
	v_pk_mul_f32 v[42:43], v[42:43], v[138:139]
	v_pk_mul_f32 v[38:39], v[38:39], v[142:143]
	v_pk_mul_f32 v[34:35], v[34:35], v[146:147]
	v_pk_mul_f32 v[32:33], v[32:33], v[144:145]
	v_pk_mul_f32 v[28:29], v[28:29], v[132:133]
	v_pk_mul_f32 v[24:25], v[24:25], v[136:137]
	v_pk_mul_f32 v[20:21], v[20:21], v[140:141]
	v_pk_mul_f32 v[30:31], v[30:31], v[134:135]
	v_pk_mul_f32 v[26:27], v[26:27], v[138:139]
	v_pk_mul_f32 v[22:23], v[22:23], v[142:143]
	v_pk_mul_f32 v[18:19], v[18:19], v[146:147]
	v_pk_mul_f32 v[16:17], v[16:17], v[144:145]
	v_pk_mul_f32 v[12:13], v[12:13], v[132:133]
	v_pk_mul_f32 v[8:9], v[8:9], v[136:137]
	v_pk_mul_f32 v[4:5], v[4:5], v[140:141]
	v_pk_mul_f32 v[14:15], v[14:15], v[134:135]
	v_pk_mul_f32 v[10:11], v[10:11], v[138:139]
	v_pk_mul_f32 v[6:7], v[6:7], v[142:143]
	v_pk_mul_f32 v[2:3], v[2:3], v[146:147]
	v_pk_mul_f32 v[0:1], v[0:1], v[144:145]

; __device__ __forceinline__ void partialSM(f32x16& p0, f32x16& p1, float& m_reg, float& mn, float& alpha, const float C, const float thr) {
;     ...
;     else { mn = fmaxf(m_reg, pmax); alpha = __builtin_amdgcn_exp2f((m_reg - mn) * C); m_reg = mn; }
;     const float mnC = -mn * C;
; #pragma unroll
;     for (int r = 0; r < 16; ++r) p0[r] = fmaf(p0[r], C, mnC);
; #pragma unroll
;     for (int r = 0; r < 16; ++r) p1[r] = fmaf(p1[r], C, mnC);
; #pragma unroll
;     for (int r = 0; r < 16; ++r) p0[r] = __builtin_amdgcn_exp2f(p0[r]);
; }
; __device__ __forceinline__ void finishSM(f32x16& p0, f32x16& p1, float alpha, float& l_reg, bf16x8& pa0, bf16x8& pa1, bf16x8& pa2, bf16x8& pa3) {
; #pragma unroll
;     for (int r = 0; r < 16; ++r) p1[r] = __builtin_amdgcn_exp2f(p1[r]);
;     float ps = 0;
; #pragma unroll
;     for (int r = 0; r < 16; ++r) ps += p0[r];
; #pragma unroll
;     for (int r = 0; r < 16; ++r) ps += p1[r];
;     { auto rr = __builtin_amdgcn_permlane32_swap(__float_as_uint(ps), __float_as_uint(ps), false, false);
;       ps = __uint_as_float(rr[0]) + __uint_as_float(rr[1]); }
;     l_reg = l_reg * alpha + ps;
; template <int DQK, int DK1, int LDQ, int LDK, int LDKR, int LDV, int NQL, int SDEPTH>
; __device__ __forceinline__ void attn_core(const AttnArgs& a, char* lds, f32x16 (&o)[4]) {
;     ...
;     for (int j = 1; j + 1 < NT; j += 2) {
.LBB0_227:
	v_cndmask_b32_e64 v204, v130, v204, s[14:15]
	v_mul_f32_e32 v136, 0xbdd53b94, v204
	v_mov_b32_e32 v137, v136
	v_fmamk_f32 v80, v80, 0x3dd53b94, v136
	v_fmamk_f32 v81, v81, 0x3dd53b94, v136
	v_fmamk_f32 v82, v82, 0x3dd53b94, v136
	v_fmamk_f32 v83, v83, 0x3dd53b94, v136
	v_fmamk_f32 v84, v84, 0x3dd53b94, v136
	v_fmamk_f32 v85, v85, 0x3dd53b94, v136
	v_fmamk_f32 v86, v86, 0x3dd53b94, v136
	v_fmamk_f32 v87, v87, 0x3dd53b94, v136
	v_fmamk_f32 v88, v88, 0x3dd53b94, v136
	v_fmamk_f32 v89, v89, 0x3dd53b94, v136
	v_fmamk_f32 v90, v90, 0x3dd53b94, v136
	v_fmamk_f32 v91, v91, 0x3dd53b94, v136
	v_fmamk_f32 v92, v92, 0x3dd53b94, v136
	v_fmamk_f32 v93, v93, 0x3dd53b94, v136
	v_fmamk_f32 v94, v94, 0x3dd53b94, v136
	v_fmac_f32_e32 v137, 0x3dd53b94, v95
	v_exp_f32_e32 v219, v80
	v_exp_f32_e32 v221, v81
	v_exp_f32_e32 v157, v82
	v_exp_f32_e32 v220, v83
	v_exp_f32_e32 v156, v84
	v_exp_f32_e32 v218, v85
	v_exp_f32_e32 v154, v86
	v_exp_f32_e32 v155, v87
	v_exp_f32_e32 v151, v88
	v_exp_f32_e32 v153, v89
	v_exp_f32_e32 v150, v90
	v_exp_f32_e32 v152, v91
	v_exp_f32_e32 v147, v92
	v_exp_f32_e32 v149, v93
	v_exp_f32_e32 v146, v94
	v_exp_f32_e32 v148, v137
	v_pk_fma_f32 v[142:143], v[64:65], s[60:61], v[136:137] op_sel_hi:[1,0,0]
	v_add_f32_e32 v64, v222, v223
	v_fmac_f32_e32 v64, v217, v182
	v_add_f32_e32 v182, v226, v227
	s_addk_i32 s37, 0x80
	s_add_i32 s69, s38, 1
	v_pk_fma_f32 v[140:141], v[66:67], s[60:61], v[136:137] op_sel_hi:[1,0,0]
	v_pk_fma_f32 v[134:135], v[68:69], s[60:61], v[136:137] op_sel_hi:[1,0,0]
	v_pk_fma_f32 v[132:133], v[70:71], s[60:61], v[136:137] op_sel_hi:[1,0,0]
	v_pk_fma_f32 v[130:131], v[72:73], s[60:61], v[136:137] op_sel_hi:[1,0,0]
	v_pk_fma_f32 v[144:145], v[74:75], s[60:61], v[136:137] op_sel_hi:[1,0,0]
	v_pk_fma_f32 v[138:139], v[76:77], s[60:61], v[136:137] op_sel_hi:[1,0,0]
	v_pk_fma_f32 v[136:137], v[78:79], s[60:61], v[136:137] op_sel_hi:[1,0,0]
	v_fmac_f32_e32 v182, v64, v225
	s_cmp_ge_u32 s69, s29
	s_waitcnt lgkmcnt(0)
	s_cbranch_scc1 .Lrot_x219
	v_mov_b32_e32 v217, v224
	s_branch .LBB0_219
